# diff-attn max-reduce via permlane16/32_swap + max3 tree (drop ds_bpermute chain)
# speedup vs baseline: 1.0135x; 1.0135x over previous
.LBB0_50:
	v_max3_f32 v194, v166, v167, v168
	v_max3_f32 v195, v169, v162, v163
	v_max3_f32 v196, v164, v165, v158
	v_max3_f32 v194, v194, v159, v160
	v_max3_f32 v195, v195, v161, v154
	v_max3_f32 v196, v196, v155, v156
	v_max3_f32 v194, v194, v195, v157
	v_max_f32_e32 v194, v194, v196
	v_max3_f32 v195, v150, v151, v152
	v_max3_f32 v196, v153, v146, v147
	v_max3_f32 v199, v148, v149, v142
	v_max3_f32 v195, v195, v143, v144
	v_max3_f32 v196, v196, v145, v138
	v_max3_f32 v199, v199, v139, v140
	v_max3_f32 v195, v195, v196, v141
	v_max_f32_e32 v195, v195, v199
	v_mov_b32_e32 v196, v194
	v_mov_b32_e32 v199, v195
	s_nop 1
	v_permlane16_swap_b32_e32 v194, v196
	v_permlane16_swap_b32_e32 v195, v199
	v_max_f32_e32 v194, v194, v196
	v_max_f32_e32 v195, v195, v199
	v_mov_b32_e32 v196, v194
	v_mov_b32_e32 v199, v195
	s_nop 1
	v_permlane32_swap_b32_e32 v194, v196
	v_permlane32_swap_b32_e32 v195, v199
	v_max3_f32 v201, v198, v195, v199
	v_max3_f32 v199, v200, v194, v196
	v_cmp_gt_f32_e32 vcc, v199, v200
	v_cmp_gt_f32_e64 s[40:41], v201, v198
	s_or_b64 vcc, vcc, s[40:41]
	s_cbranch_vccz .LBB0_52
	v_sub_f32_e32 v194, v200, v199
	v_mul_f32_e32 v194, 0x3e38aa3b, v194
	v_exp_f32_e32 v194, v194
	s_nop 0
	v_pk_mul_f32 v[92:93], v[92:93], v[194:195] op_sel_hi:[1,0]
	v_pk_mul_f32 v[90:91], v[90:91], v[194:195] op_sel_hi:[1,0]
	v_pk_mul_f32 v[104:105], v[104:105], v[194:195] op_sel_hi:[1,0]
	v_pk_mul_f32 v[102:103], v[102:103], v[194:195] op_sel_hi:[1,0]
	v_pk_mul_f32 v[100:101], v[100:101], v[194:195] op_sel_hi:[1,0]
	v_pk_mul_f32 v[98:99], v[98:99], v[194:195] op_sel_hi:[1,0]
	v_pk_mul_f32 v[96:97], v[96:97], v[194:195] op_sel_hi:[1,0]
	v_pk_mul_f32 v[94:95], v[94:95], v[194:195] op_sel_hi:[1,0]
	v_pk_mul_f32 v[88:89], v[88:89], v[194:195] op_sel_hi:[1,0]
	v_pk_mul_f32 v[86:87], v[86:87], v[194:195] op_sel_hi:[1,0]
	v_pk_mul_f32 v[84:85], v[84:85], v[194:195] op_sel_hi:[1,0]
	v_pk_mul_f32 v[82:83], v[82:83], v[194:195] op_sel_hi:[1,0]
	v_pk_mul_f32 v[80:81], v[80:81], v[194:195] op_sel_hi:[1,0]
	v_pk_mul_f32 v[78:79], v[78:79], v[194:195] op_sel_hi:[1,0]
	v_pk_mul_f32 v[76:77], v[76:77], v[194:195] op_sel_hi:[1,0]
	v_pk_mul_f32 v[74:75], v[74:75], v[194:195] op_sel_hi:[1,0]
	v_sub_f32_e32 v195, v198, v201
	v_mul_f32_e32 v195, 0x3e38aa3b, v195
	v_exp_f32_e32 v195, v195
	s_nop 0
	v_pk_mul_f32 v[178:179], v[178:179], v[194:195]
	v_mov_b32_e32 v194, v195
	v_pk_mul_f32 v[72:73], v[72:73], v[194:195] op_sel_hi:[1,0]
	v_pk_mul_f32 v[70:71], v[70:71], v[194:195] op_sel_hi:[1,0]
	v_pk_mul_f32 v[68:69], v[68:69], v[194:195] op_sel_hi:[1,0]
	v_pk_mul_f32 v[66:67], v[66:67], v[194:195] op_sel_hi:[1,0]
	v_pk_mul_f32 v[60:61], v[60:61], v[194:195] op_sel_hi:[1,0]
	v_pk_mul_f32 v[58:59], v[58:59], v[194:195] op_sel_hi:[1,0]
	v_pk_mul_f32 v[56:57], v[56:57], v[194:195] op_sel_hi:[1,0]
	v_pk_mul_f32 v[54:55], v[54:55], v[194:195] op_sel_hi:[1,0]
	v_pk_mul_f32 v[48:49], v[48:49], v[194:195] op_sel_hi:[1,0]
	v_pk_mul_f32 v[46:47], v[46:47], v[194:195] op_sel_hi:[1,0]
	v_pk_mul_f32 v[40:41], v[40:41], v[194:195] op_sel_hi:[1,0]
	v_pk_mul_f32 v[38:39], v[38:39], v[194:195] op_sel_hi:[1,0]
	v_pk_mul_f32 v[36:37], v[36:37], v[194:195] op_sel_hi:[1,0]
	v_pk_mul_f32 v[34:35], v[34:35], v[194:195] op_sel_hi:[1,0]
	v_pk_mul_f32 v[28:29], v[28:29], v[194:195] op_sel_hi:[1,0]
	v_pk_mul_f32 v[26:27], v[26:27], v[194:195] op_sel_hi:[1,0]
